# GEMM K-loop: first iteration of every unit peeled with C=0 on each accumulator's first MFMA; the 128 per-unit accumulator-zeroing moves are gone
# speedup vs baseline: 1.0657x; 1.0044x over previous
; #define PG8_STAGE(bufoff, gbase, voff) do { _Pragma("unroll") for (int _i = 0; _i < 2; ++_i) \
;         __builtin_amdgcn_global_load_lds((const unsigned*)((const char*)(gbase) + (voff)[_i]), (PG8_LAS unsigned*)(lds + (bufoff) + ldsw + _i * 8192), 16, 0, 0); } while (0)
; #define PG8_LDA(dst, b, h) do { _Pragma("unroll") for (int m = 0; m < 4; ++m) _Pragma("unroll") for (int k = 0; k < 2; ++k) dst[m][k] = *(const PG8_LAS bf16x8*)(lds + PG8_SA(b, h) + aoff + m * 2048 + k * 1024); } while (0)
; #define PG8_LDB(dst, b, h) do { _Pragma("unroll") for (int n = 0; n < 2; ++n) _Pragma("unroll") for (int k = 0; k < 2; ++k) dst[n][k] = *(const PG8_LAS bf16x8*)(lds + PG8_SB(b, h) + boff + n * 2048 + k * 1024); } while (0)
; #define PG8_MMA(ai, bj, At, Bt) do { __builtin_amdgcn_s_setprio(1); _Pragma("unroll") for (int m = 0; m < 4; ++m) _Pragma("unroll") for (int n = 0; n < 2; ++n) _Pragma("unroll") for (int k = 0; k < 2; ++k) \
;         acc[ai][bj][m][n] = __builtin_amdgcn_mfma_f32_16x16x32_bf16(Bt[n][k], At[m][k], acc[ai][bj][m][n], 0, 0, 0); __builtin_amdgcn_s_setprio(0); } while (0)
; #define PG8_WAIT_V(n) asm volatile("s_waitcnt vmcnt(" #n ")" ::: "memory")
; #define PG8_BAR __builtin_amdgcn_s_barrier()
; template <class Epi, class Sched, bool ALIGN_EPI = false, bool SP2 = false>
; __device__ __forceinline__ void gemm_phase(PG8_LAS unsigned char* lds, const Gemm g, const Sched& S, const Epi& E) {
;     ...
;         for (int t = 0; t < nt; t += 2) {
;             const bool last = (t == nt - 2);
;             const char* a1 = cA + (size_t)(t + 1) * kstep;
;             const char* a2 = last ? nA : cA + (size_t)(t + 2) * kstep; const char* b2 = last ? nB : cB + (size_t)(t + 2) * kstep;
;             const char* a3 = a2 + kstep; const char* b3 = b2 + kstep;
;             if (last && has_next) S.a_ready(nxt);
;             if constexpr (SP2) {
;             PG8_LDB(B0, 0, 0); PG8_LDB(B1, 0, 1); PG8_SCHED; PG8_LDA(At, 0, 0); PG8_STAGE(PG8_SA(1, 1), a1 + hstepA, voffA);
;             PG8_WAIT_V(8); PG8_WAIT_L(0); PG8_BAR; PG8_MMA(0, 0, At, B0); PG8_MMA(0, 1, At, B1); PG8_BAR; PG8_SCHED;
;             PG8_LDA(At, 0, 1); PG8_STAGE(PG8_SB(0, 0), b2, voffB); PG8_STAGE(PG8_SB(0, 1), b2 + hstep, voffB); PG8_STAGE(PG8_SA(0, 0), a2, voffA);
;             PG8_WAIT_V(8); PG8_WAIT_L(0); PG8_BAR; PG8_MMA(1, 0, At, B0); PG8_MMA(1, 1, At, B1); PG8_BAR; PG8_SCHED;
.LBB0_486:
	s_add_i32 s20, s62, -2
	s_add_u32 s44, s44, 0x80
	s_addc_u32 s45, s45, 0
	s_add_u32 s21, s46, 0x100
	s_addc_u32 s40, s47, 0
	s_mov_b32 s24, 0
	s_add_i32 s41, s24, 2
	s_add_u32 s22, s44, 0x80
	s_addc_u32 s23, s45, 0
	s_add_i32 s48, 0, 0x10000
	s_cmp_eq_u32 s20, s24
	s_cselect_b32 s25, s75, s23
	s_cselect_b32 s24, s74, s22
	v_add_u32_e32 v112, s48, v176
	s_cselect_b32 s47, s69, s40
	s_cselect_b32 s46, s68, s21
	s_add_i32 s22, 0, 0x14000
	ds_read_b128 v[130:133], v112
	ds_read_b128 v[134:137], v112 offset:1024
	ds_read_b128 v[138:141], v112 offset:2048
	ds_read_b128 v[154:157], v112 offset:3072
	v_add_u32_e32 v112, s22, v176
	ds_read_b128 v[158:161], v112
	ds_read_b128 v[162:165], v112 offset:1024
	ds_read_b128 v[166:169], v112 offset:2048
	ds_read_b128 v[170:173], v112 offset:3072
	v_lshl_add_u64 v[174:175], s[44:45], 0, v[150:151]
	s_add_i32 m0, s33, 0xc000
	ds_read_b128 v[188:191], v177
	ds_read_b128 v[192:195], v177 offset:1024
	ds_read_b128 v[196:199], v177 offset:2048
	ds_read_b128 v[200:203], v177 offset:3072
	ds_read_b128 v[204:207], v177 offset:4096
	ds_read_b128 v[216:219], v177 offset:5120
	ds_read_b128 v[220:223], v177 offset:6144
	ds_read_b128 v[224:227], v177 offset:7168
	global_load_lds_dwordx4 v[174:175], off
	v_lshl_add_u64 v[174:175], s[44:45], 0, v[152:153]
	s_add_i32 m0, s33, 0xe000
	s_nop 0
	global_load_lds_dwordx4 v[174:175], off
	s_waitcnt vmcnt(8)
	s_waitcnt lgkmcnt(0)
	s_barrier
	s_setprio 1
	s_waitcnt lgkmcnt(0)
	v_mfma_f32_16x16x32_bf16 v[126:129], v[130:133], v[188:191], 0
	v_mfma_f32_16x16x32_bf16 v[122:125], v[138:141], v[188:191], 0
	v_mfma_f32_16x16x32_bf16 v[108:111], v[130:133], v[196:199], 0
	v_mfma_f32_16x16x32_bf16 v[104:107], v[138:141], v[196:199], 0
	v_mfma_f32_16x16x32_bf16 v[92:95], v[130:133], v[204:207], 0
	v_mfma_f32_16x16x32_bf16 v[88:91], v[138:141], v[204:207], 0
	v_mfma_f32_16x16x32_bf16 v[76:79], v[130:133], v[220:223], 0
	v_mfma_f32_16x16x32_bf16 v[72:75], v[138:141], v[220:223], 0
	v_mfma_f32_16x16x32_bf16 v[126:129], v[134:137], v[192:195], v[126:129]
	v_mfma_f32_16x16x32_bf16 v[122:125], v[154:157], v[192:195], v[122:125]
	v_mfma_f32_16x16x32_bf16 v[108:111], v[134:137], v[200:203], v[108:111]
	v_mfma_f32_16x16x32_bf16 v[104:107], v[154:157], v[200:203], v[104:107]
	v_mfma_f32_16x16x32_bf16 v[92:95], v[134:137], v[216:219], v[92:95]
	v_mfma_f32_16x16x32_bf16 v[88:91], v[154:157], v[216:219], v[88:91]
	v_mfma_f32_16x16x32_bf16 v[76:79], v[134:137], v[224:227], v[76:79]
	v_mfma_f32_16x16x32_bf16 v[72:75], v[154:157], v[224:227], v[72:75]
	s_setprio 0
	s_setprio 1
	v_mfma_f32_16x16x32_bf16 v[118:121], v[158:161], v[188:191], 0
	v_mfma_f32_16x16x32_bf16 v[114:117], v[166:169], v[188:191], 0
	v_mfma_f32_16x16x32_bf16 v[100:103], v[158:161], v[196:199], 0
	v_mfma_f32_16x16x32_bf16 v[96:99], v[166:169], v[196:199], 0
	v_mfma_f32_16x16x32_bf16 v[84:87], v[158:161], v[204:207], 0
	v_mfma_f32_16x16x32_bf16 v[80:83], v[166:169], v[204:207], 0
	v_mfma_f32_16x16x32_bf16 v[68:71], v[158:161], v[220:223], 0
	v_mfma_f32_16x16x32_bf16 v[64:67], v[166:169], v[220:223], 0
	v_mfma_f32_16x16x32_bf16 v[118:121], v[162:165], v[192:195], v[118:121]
	v_mfma_f32_16x16x32_bf16 v[114:117], v[170:173], v[192:195], v[114:117]
	v_mfma_f32_16x16x32_bf16 v[100:103], v[162:165], v[200:203], v[100:103]
	v_mfma_f32_16x16x32_bf16 v[96:99], v[170:173], v[200:203], v[96:99]
	v_mfma_f32_16x16x32_bf16 v[84:87], v[162:165], v[216:219], v[84:87]
	v_mfma_f32_16x16x32_bf16 v[80:83], v[170:173], v[216:219], v[80:83]
	v_mfma_f32_16x16x32_bf16 v[68:71], v[162:165], v[224:227], v[68:71]
	v_mfma_f32_16x16x32_bf16 v[64:67], v[170:173], v[224:227], v[64:67]
	s_setprio 0
	s_barrier
	s_add_i32 s23, s48, s39
	v_lshl_add_u64 v[174:175], s[46:47], 0, v[144:145]
	s_mov_b32 m0, s23
	ds_read_b128 v[188:191], v177 offset:16384
	ds_read_b128 v[192:195], v177 offset:17408
	ds_read_b128 v[196:199], v177 offset:18432
	ds_read_b128 v[200:203], v177 offset:19456
	ds_read_b128 v[204:207], v177 offset:20480
	ds_read_b128 v[216:219], v177 offset:21504
	ds_read_b128 v[220:223], v177 offset:22528
	ds_read_b128 v[224:227], v177 offset:23552
	global_load_lds_dwordx4 v[174:175], off
	s_add_i32 m0, s23, 0x2000
	v_lshl_add_u64 v[178:179], s[46:47], 0, v[148:149]
	s_add_u32 s46, s46, s8
	s_addc_u32 s47, s47, s9
	s_add_i32 s22, s22, s39
	global_load_lds_dwordx4 v[178:179], off
	v_lshl_add_u64 v[212:213], s[46:47], 0, v[144:145]
	s_mov_b32 m0, s22
	v_lshl_add_u64 v[214:215], s[46:47], 0, v[148:149]
	global_load_lds_dwordx4 v[212:213], off
	s_add_i32 m0, s22, 0x2000
	v_lshl_add_u64 v[228:229], s[24:25], 0, v[142:143]
	global_load_lds_dwordx4 v[214:215], off
	s_mov_b32 m0, s33
	v_lshl_add_u64 v[230:231], s[24:25], 0, v[146:147]
	global_load_lds_dwordx4 v[228:229], off
	s_mov_b32 m0, s37
	s_nop 0
	global_load_lds_dwordx4 v[230:231], off
	s_waitcnt vmcnt(8)
	s_waitcnt lgkmcnt(0)
	s_barrier
; #define PG8_STAGE(bufoff, gbase, voff) do { _Pragma("unroll") for (int _i = 0; _i < 2; ++_i) \
;         __builtin_amdgcn_global_load_lds((const unsigned*)((const char*)(gbase) + (voff)[_i]), (PG8_LAS unsigned*)(lds + (bufoff) + ldsw + _i * 8192), 16, 0, 0); } while (0)
; #define PG8_LDA(dst, b, h) do { _Pragma("unroll") for (int m = 0; m < 4; ++m) _Pragma("unroll") for (int k = 0; k < 2; ++k) dst[m][k] = *(const PG8_LAS bf16x8*)(lds + PG8_SA(b, h) + aoff + m * 2048 + k * 1024); } while (0)
; #define PG8_LDB(dst, b, h) do { _Pragma("unroll") for (int n = 0; n < 2; ++n) _Pragma("unroll") for (int k = 0; k < 2; ++k) dst[n][k] = *(const PG8_LAS bf16x8*)(lds + PG8_SB(b, h) + boff + n * 2048 + k * 1024); } while (0)
; #define PG8_MMA(ai, bj, At, Bt) do { __builtin_amdgcn_s_setprio(1); _Pragma("unroll") for (int m = 0; m < 4; ++m) _Pragma("unroll") for (int n = 0; n < 2; ++n) _Pragma("unroll") for (int k = 0; k < 2; ++k) \
;         acc[ai][bj][m][n] = __builtin_amdgcn_mfma_f32_16x16x32_bf16(Bt[n][k], At[m][k], acc[ai][bj][m][n], 0, 0, 0); __builtin_amdgcn_s_setprio(0); } while (0)
; #define PG8_WAIT_V(n) asm volatile("s_waitcnt vmcnt(" #n ")" ::: "memory")
; #define PG8_WAIT_L(n) asm volatile("s_waitcnt lgkmcnt(" #n ")" ::: "memory")
; #define PG8_BAR __builtin_amdgcn_s_barrier()
; #define PG8_SCHED __builtin_amdgcn_sched_barrier(0)
; template <class Epi, class Sched, bool ALIGN_EPI = false, bool SP2 = false>
; __device__ __forceinline__ void gemm_phase(PG8_LAS unsigned char* lds, const Gemm g, const Sched& S, const Epi& E) {
;     ...
;             PG8_LDB(B0, 0, 0); PG8_LDB(B1, 0, 1); PG8_SCHED; PG8_LDA(At, 0, 0); PG8_STAGE(PG8_SA(1, 1), a1 + hstepA, voffA);
;             PG8_WAIT_V(8); PG8_WAIT_L(0); PG8_BAR; PG8_MMA(0, 0, At, B0); PG8_MMA(0, 1, At, B1); PG8_BAR; PG8_SCHED;
;             PG8_LDA(At, 0, 1); PG8_STAGE(PG8_SB(0, 0), b2, voffB); PG8_STAGE(PG8_SB(0, 1), b2 + hstep, voffB); PG8_STAGE(PG8_SA(0, 0), a2, voffA);
;             PG8_WAIT_V(8); PG8_WAIT_L(0); PG8_BAR; PG8_MMA(1, 0, At, B0); PG8_MMA(1, 1, At, B1); PG8_BAR; PG8_SCHED;
;             PG8_LDB(B0, 1, 0); PG8_LDB(B1, 1, 1); PG8_SCHED; PG8_LDA(At, 1, 0); PG8_STAGE(PG8_SA(0, 1), a2 + hstepA, voffA);
;             PG8_WAIT_V(8); PG8_WAIT_L(0); PG8_BAR; PG8_MMA(0, 0, At, B0); PG8_MMA(0, 1, At, B1); PG8_BAR; PG8_SCHED;
	s_setprio 1
	s_waitcnt lgkmcnt(0)
	v_mfma_f32_16x16x32_bf16 v[60:63], v[130:133], v[188:191], 0
	v_mfma_f32_16x16x32_bf16 v[56:59], v[138:141], v[188:191], 0
	v_mfma_f32_16x16x32_bf16 v[44:47], v[130:133], v[196:199], 0
	v_mfma_f32_16x16x32_bf16 v[40:43], v[138:141], v[196:199], 0
	v_mfma_f32_16x16x32_bf16 v[28:31], v[130:133], v[204:207], 0
	v_mfma_f32_16x16x32_bf16 v[24:27], v[138:141], v[204:207], 0
	v_mfma_f32_16x16x32_bf16 v[12:15], v[130:133], v[220:223], 0
	v_mfma_f32_16x16x32_bf16 v[8:11], v[138:141], v[220:223], 0
	v_mfma_f32_16x16x32_bf16 v[60:63], v[134:137], v[192:195], v[60:63]
	v_mfma_f32_16x16x32_bf16 v[56:59], v[154:157], v[192:195], v[56:59]
	v_mfma_f32_16x16x32_bf16 v[44:47], v[134:137], v[200:203], v[44:47]
	v_mfma_f32_16x16x32_bf16 v[40:43], v[154:157], v[200:203], v[40:43]
	v_mfma_f32_16x16x32_bf16 v[28:31], v[134:137], v[216:219], v[28:31]
	v_mfma_f32_16x16x32_bf16 v[24:27], v[154:157], v[216:219], v[24:27]
	v_mfma_f32_16x16x32_bf16 v[12:15], v[134:137], v[224:227], v[12:15]
	v_mfma_f32_16x16x32_bf16 v[8:11], v[154:157], v[224:227], v[8:11]
	s_setprio 0
	s_setprio 1
	v_mfma_f32_16x16x32_bf16 v[52:55], v[158:161], v[188:191], 0
	v_mfma_f32_16x16x32_bf16 v[48:51], v[166:169], v[188:191], 0
	v_mfma_f32_16x16x32_bf16 v[36:39], v[158:161], v[196:199], 0
	v_mfma_f32_16x16x32_bf16 v[32:35], v[166:169], v[196:199], 0
	v_mfma_f32_16x16x32_bf16 v[20:23], v[158:161], v[204:207], 0
	v_mfma_f32_16x16x32_bf16 v[16:19], v[166:169], v[204:207], 0
	v_mfma_f32_16x16x32_bf16 v[4:7], v[158:161], v[220:223], 0
	v_mfma_f32_16x16x32_bf16 v[0:3], v[166:169], v[220:223], 0
	v_mfma_f32_16x16x32_bf16 v[52:55], v[162:165], v[192:195], v[52:55]
	v_mfma_f32_16x16x32_bf16 v[48:51], v[170:173], v[192:195], v[48:51]
	v_mfma_f32_16x16x32_bf16 v[36:39], v[162:165], v[200:203], v[36:39]
	v_mfma_f32_16x16x32_bf16 v[32:35], v[170:173], v[200:203], v[32:35]
	v_mfma_f32_16x16x32_bf16 v[20:23], v[162:165], v[216:219], v[20:23]
	v_mfma_f32_16x16x32_bf16 v[16:19], v[170:173], v[216:219], v[16:19]
	v_mfma_f32_16x16x32_bf16 v[4:7], v[162:165], v[224:227], v[4:7]
	v_mfma_f32_16x16x32_bf16 v[0:3], v[170:173], v[224:227], v[0:3]
	s_setprio 0
	s_barrier
	s_add_i32 s22, 0, 0x18000
	v_add_u32_e32 v112, s22, v176
	s_add_i32 s23, 0, 0x1c000
	ds_read_b128 v[130:133], v112
	ds_read_b128 v[134:137], v112 offset:1024
	ds_read_b128 v[138:141], v112 offset:2048
	ds_read_b128 v[154:157], v112 offset:3072
	v_add_u32_e32 v112, s23, v176
	ds_read_b128 v[158:161], v112
	ds_read_b128 v[162:165], v112 offset:1024
	ds_read_b128 v[166:169], v112 offset:2048
	ds_read_b128 v[170:173], v112 offset:3072
	s_add_u32 s24, s24, s12
	s_addc_u32 s25, s25, s13
	s_mov_b32 m0, s50
	v_lshl_add_u64 v[232:233], s[24:25], 0, v[142:143]
	ds_read_b128 v[188:191], v177 offset:32768
	ds_read_b128 v[192:195], v177 offset:33792
	ds_read_b128 v[196:199], v177 offset:34816
	ds_read_b128 v[200:203], v177 offset:35840
	ds_read_b128 v[204:207], v177 offset:36864
	ds_read_b128 v[216:219], v177 offset:37888
	ds_read_b128 v[220:223], v177 offset:38912
	ds_read_b128 v[224:227], v177 offset:39936
	global_load_lds_dwordx4 v[232:233], off
	v_lshl_add_u64 v[232:233], s[24:25], 0, v[146:147]
	s_mov_b32 m0, s51
	s_nop 0
	global_load_lds_dwordx4 v[232:233], off
	s_waitcnt vmcnt(8)
	s_waitcnt lgkmcnt(0)
	s_barrier
	s_setprio 1
	s_waitcnt lgkmcnt(0)
	v_mfma_f32_16x16x32_bf16 v[126:129], v[130:133], v[188:191], v[126:129]
	v_mfma_f32_16x16x32_bf16 v[122:125], v[138:141], v[188:191], v[122:125]
	v_mfma_f32_16x16x32_bf16 v[108:111], v[130:133], v[196:199], v[108:111]
	v_mfma_f32_16x16x32_bf16 v[104:107], v[138:141], v[196:199], v[104:107]
	v_mfma_f32_16x16x32_bf16 v[92:95], v[130:133], v[204:207], v[92:95]
	v_mfma_f32_16x16x32_bf16 v[88:91], v[138:141], v[204:207], v[88:91]
	v_mfma_f32_16x16x32_bf16 v[76:79], v[130:133], v[220:223], v[76:79]
	v_mfma_f32_16x16x32_bf16 v[72:75], v[138:141], v[220:223], v[72:75]
	v_mfma_f32_16x16x32_bf16 v[126:129], v[134:137], v[192:195], v[126:129]
	v_mfma_f32_16x16x32_bf16 v[122:125], v[154:157], v[192:195], v[122:125]
	v_mfma_f32_16x16x32_bf16 v[108:111], v[134:137], v[200:203], v[108:111]
	v_mfma_f32_16x16x32_bf16 v[104:107], v[154:157], v[200:203], v[104:107]
	v_mfma_f32_16x16x32_bf16 v[92:95], v[134:137], v[216:219], v[92:95]
	v_mfma_f32_16x16x32_bf16 v[88:91], v[154:157], v[216:219], v[88:91]
	v_mfma_f32_16x16x32_bf16 v[76:79], v[134:137], v[224:227], v[76:79]
	v_mfma_f32_16x16x32_bf16 v[72:75], v[154:157], v[224:227], v[72:75]
	s_setprio 0
	s_setprio 1
	v_mfma_f32_16x16x32_bf16 v[118:121], v[158:161], v[188:191], v[118:121]
	v_mfma_f32_16x16x32_bf16 v[114:117], v[166:169], v[188:191], v[114:117]
	v_mfma_f32_16x16x32_bf16 v[100:103], v[158:161], v[196:199], v[100:103]
	v_mfma_f32_16x16x32_bf16 v[96:99], v[166:169], v[196:199], v[96:99]
	v_mfma_f32_16x16x32_bf16 v[84:87], v[158:161], v[204:207], v[84:87]
	v_mfma_f32_16x16x32_bf16 v[80:83], v[166:169], v[204:207], v[80:83]
	v_mfma_f32_16x16x32_bf16 v[68:71], v[158:161], v[220:223], v[68:71]
	v_mfma_f32_16x16x32_bf16 v[64:67], v[166:169], v[220:223], v[64:67]
	v_mfma_f32_16x16x32_bf16 v[118:121], v[162:165], v[192:195], v[118:121]
	v_mfma_f32_16x16x32_bf16 v[114:117], v[170:173], v[192:195], v[114:117]
	v_mfma_f32_16x16x32_bf16 v[100:103], v[162:165], v[200:203], v[100:103]
	v_mfma_f32_16x16x32_bf16 v[96:99], v[170:173], v[200:203], v[96:99]
	v_mfma_f32_16x16x32_bf16 v[84:87], v[162:165], v[216:219], v[84:87]
	v_mfma_f32_16x16x32_bf16 v[80:83], v[170:173], v[216:219], v[80:83]
	v_mfma_f32_16x16x32_bf16 v[68:71], v[162:165], v[224:227], v[68:71]
	v_mfma_f32_16x16x32_bf16 v[64:67], v[170:173], v[224:227], v[64:67]
	s_setprio 0
	s_barrier
; #define PG8_STAGE(bufoff, gbase, voff) do { _Pragma("unroll") for (int _i = 0; _i < 2; ++_i) \
;         __builtin_amdgcn_global_load_lds((const unsigned*)((const char*)(gbase) + (voff)[_i]), (PG8_LAS unsigned*)(lds + (bufoff) + ldsw + _i * 8192), 16, 0, 0); } while (0)
; #define PG8_LDA(dst, b, h) do { _Pragma("unroll") for (int m = 0; m < 4; ++m) _Pragma("unroll") for (int k = 0; k < 2; ++k) dst[m][k] = *(const PG8_LAS bf16x8*)(lds + PG8_SA(b, h) + aoff + m * 2048 + k * 1024); } while (0)
; #define PG8_MMA(ai, bj, At, Bt) do { __builtin_amdgcn_s_setprio(1); _Pragma("unroll") for (int m = 0; m < 4; ++m) _Pragma("unroll") for (int n = 0; n < 2; ++n) _Pragma("unroll") for (int k = 0; k < 2; ++k) \
;         acc[ai][bj][m][n] = __builtin_amdgcn_mfma_f32_16x16x32_bf16(Bt[n][k], At[m][k], acc[ai][bj][m][n], 0, 0, 0); __builtin_amdgcn_s_setprio(0); } while (0)
; #define PG8_WAIT_V(n) asm volatile("s_waitcnt vmcnt(" #n ")" ::: "memory")
; #define PG8_WAIT_L(n) asm volatile("s_waitcnt lgkmcnt(" #n ")" ::: "memory")
; #define PG8_BAR __builtin_amdgcn_s_barrier()
; #define PG8_SCHED __builtin_amdgcn_sched_barrier(0)
; template <class Epi, class Sched, bool ALIGN_EPI = false, bool SP2 = false>
; __device__ __forceinline__ void gemm_phase(PG8_LAS unsigned char* lds, const Gemm g, const Sched& S, const Epi& E) {
;     ...
;         for (int t = 0; t < nt; t += 2) {
;             const bool last = (t == nt - 2);
;             const char* a1 = cA + (size_t)(t + 1) * kstep;
;             const char* a2 = last ? nA : cA + (size_t)(t + 2) * kstep; const char* b2 = last ? nB : cB + (size_t)(t + 2) * kstep;
;             const char* a3 = a2 + kstep; const char* b3 = b2 + kstep;
;     ...
;             PG8_WAIT_V(8); PG8_WAIT_L(0); PG8_BAR; PG8_MMA(0, 0, At, B0); PG8_MMA(0, 1, At, B1); PG8_BAR; PG8_SCHED;
;             PG8_LDA(At, 1, 1); PG8_STAGE(PG8_SB(1, 0), b3, voffB); PG8_STAGE(PG8_SB(1, 1), b3 + hstep, voffB); PG8_STAGE(PG8_SA(1, 0), a3, voffA);
;             PG8_WAIT_V(8); PG8_WAIT_L(0); PG8_BAR; PG8_MMA(1, 0, At, B0); PG8_MMA(1, 1, At, B1); PG8_BAR; PG8_SCHED;
	s_add_i32 s22, s22, s39
	v_lshl_add_u64 v[174:175], v[174:175], 0, s[30:31]
	s_mov_b32 m0, s22
	ds_read_b128 v[188:191], v177 offset:49152
	ds_read_b128 v[192:195], v177 offset:50176
	ds_read_b128 v[196:199], v177 offset:51200
	ds_read_b128 v[200:203], v177 offset:52224
	ds_read_b128 v[204:207], v177 offset:53248
	ds_read_b128 v[216:219], v177 offset:54272
	ds_read_b128 v[220:223], v177 offset:55296
	ds_read_b128 v[224:227], v177 offset:56320
	global_load_lds_dwordx4 v[174:175], off
	v_lshl_add_u64 v[174:175], v[178:179], 0, s[30:31]
	s_add_i32 m0, s22, 0x2000
	s_add_i32 s22, s23, s39
	global_load_lds_dwordx4 v[174:175], off
	v_lshl_add_u64 v[174:175], v[212:213], 0, s[30:31]
	s_mov_b32 m0, s22
	s_nop 0
	global_load_lds_dwordx4 v[174:175], off
	v_lshl_add_u64 v[174:175], v[214:215], 0, s[30:31]
	s_add_i32 m0, s22, 0x2000
	s_nop 0
	global_load_lds_dwordx4 v[174:175], off
	v_lshl_add_u64 v[174:175], v[228:229], 0, s[30:31]
	s_mov_b32 m0, s57
	s_nop 0
	global_load_lds_dwordx4 v[174:175], off
	v_lshl_add_u64 v[174:175], v[230:231], 0, s[30:31]
	s_mov_b32 m0, s58
	s_nop 0
	global_load_lds_dwordx4 v[174:175], off
	s_waitcnt vmcnt(8)
	s_waitcnt lgkmcnt(0)
	s_barrier
	s_setprio 1
	s_waitcnt lgkmcnt(0)
	v_mfma_f32_16x16x32_bf16 v[60:63], v[130:133], v[188:191], v[60:63]
	v_mfma_f32_16x16x32_bf16 v[56:59], v[138:141], v[188:191], v[56:59]
	v_mfma_f32_16x16x32_bf16 v[44:47], v[130:133], v[196:199], v[44:47]
	v_mfma_f32_16x16x32_bf16 v[40:43], v[138:141], v[196:199], v[40:43]
	v_mfma_f32_16x16x32_bf16 v[28:31], v[130:133], v[204:207], v[28:31]
	v_mfma_f32_16x16x32_bf16 v[24:27], v[138:141], v[204:207], v[24:27]
	v_mfma_f32_16x16x32_bf16 v[12:15], v[130:133], v[220:223], v[12:15]
	v_mfma_f32_16x16x32_bf16 v[8:11], v[138:141], v[220:223], v[8:11]
	v_mfma_f32_16x16x32_bf16 v[60:63], v[134:137], v[192:195], v[60:63]
	v_mfma_f32_16x16x32_bf16 v[56:59], v[154:157], v[192:195], v[56:59]
	v_mfma_f32_16x16x32_bf16 v[44:47], v[134:137], v[200:203], v[44:47]
	v_mfma_f32_16x16x32_bf16 v[40:43], v[154:157], v[200:203], v[40:43]
	v_mfma_f32_16x16x32_bf16 v[28:31], v[134:137], v[216:219], v[28:31]
	v_mfma_f32_16x16x32_bf16 v[24:27], v[154:157], v[216:219], v[24:27]
	v_mfma_f32_16x16x32_bf16 v[12:15], v[134:137], v[224:227], v[12:15]
	v_mfma_f32_16x16x32_bf16 v[8:11], v[154:157], v[224:227], v[8:11]
	s_setprio 0
	s_setprio 1
	v_mfma_f32_16x16x32_bf16 v[52:55], v[158:161], v[188:191], v[52:55]
	v_mfma_f32_16x16x32_bf16 v[48:51], v[166:169], v[188:191], v[48:51]
	v_mfma_f32_16x16x32_bf16 v[36:39], v[158:161], v[196:199], v[36:39]
	v_mfma_f32_16x16x32_bf16 v[32:35], v[166:169], v[196:199], v[32:35]
	v_mfma_f32_16x16x32_bf16 v[20:23], v[158:161], v[204:207], v[20:23]
	v_mfma_f32_16x16x32_bf16 v[16:19], v[166:169], v[204:207], v[16:19]
	v_mfma_f32_16x16x32_bf16 v[4:7], v[158:161], v[220:223], v[4:7]
	v_mfma_f32_16x16x32_bf16 v[0:3], v[166:169], v[220:223], v[0:3]
	v_mfma_f32_16x16x32_bf16 v[52:55], v[162:165], v[192:195], v[52:55]
	v_mfma_f32_16x16x32_bf16 v[48:51], v[170:173], v[192:195], v[48:51]
	v_mfma_f32_16x16x32_bf16 v[36:39], v[162:165], v[200:203], v[36:39]
	v_mfma_f32_16x16x32_bf16 v[32:35], v[170:173], v[200:203], v[32:35]
	v_mfma_f32_16x16x32_bf16 v[20:23], v[162:165], v[216:219], v[20:23]
	v_mfma_f32_16x16x32_bf16 v[16:19], v[170:173], v[216:219], v[16:19]
	v_mfma_f32_16x16x32_bf16 v[4:7], v[162:165], v[224:227], v[4:7]
	v_mfma_f32_16x16x32_bf16 v[0:3], v[170:173], v[224:227], v[0:3]
	s_setprio 0
	s_barrier
	s_add_u32 s44, s44, 0x100
	s_addc_u32 s45, s45, 0
	s_add_u32 s21, s21, 0x100
	s_addc_u32 s40, s40, 0
	s_cmp_ge_i32 s41, s62
	s_mov_b32 s24, s41
	s_cbranch_scc1 .Lk_exit

; #define PG8_BAR __builtin_amdgcn_s_barrier()
; template <class Epi, class Sched, bool ALIGN_EPI = false, bool SP2 = false>
; __device__ __forceinline__ void gemm_phase(PG8_LAS unsigned char* lds, const Gemm g, const Sched& S, const Epi& E) {
;     ...
;         }
;         if constexpr (ALIGN_EPI) { if (wr == 0) PG8_BAR; }
;         if constexpr (!Epi::AFTER_DRAIN) { E(acc, cur, wr, wc, fr, fq); S.done(cur); }
;         if (!has_next) break;
.Lk_exit:
	s_and_b64 vcc, exec, s[18:19]
	s_cbranch_vccz .LBB0_490
